# compact hand-written in-proj epilogue for the raw*scale panels (now on the critical workgroup class)
# speedup vs baseline: 1.0191x; 1.0191x over previous
.LBB0_272:
	s_lshl_b32 s100, 1, s49
	s_and_b32 s101, s100, 0x1fa0
	s_cbranch_scc0 .Lepi_std
	s_and_b32 s101, s100, 0x180
	s_cselect_b32 s101, 0x3e38aa3b, 1.0
	v_mul_f32_e32 v172, s101, v172
	v_mul_f32_e32 v170, s101, v170
	v_mul_f32_e32 v168, s101, v168
	v_mul_f32_e32 v166, s101, v166
	v_mul_f32_e32 v162, s101, v162
	v_mul_f32_e32 v160, s101, v160
	v_mul_f32_e32 v158, s101, v158
	v_mul_f32_e32 v156, s101, v156
	v_mov_b64_e32 v[128:129], s[50:51]
	v_mad_u64_u32 v[128:129], s[100:101], v174, s70, v[128:129]
	s_lshl_b32 s100, s49, 9
	s_nop 0
	v_lshl_add_u32 v190, v144, 1, s100
	v_lshl_add_u64 v[128:129], v[128:129], 0, v[190:191]
	s_mov_b64 s[100:101], 0x1e000
	v_mul_f32_e32 v60, v60, v172
	v_mul_f32_e32 v61, v61, v172
	v_mul_f32_e32 v62, v62, v172
	v_mul_f32_e32 v63, v63, v172
	v_mul_f32_e32 v56, v56, v172
	v_mul_f32_e32 v57, v57, v172
	v_mul_f32_e32 v58, v58, v172
	v_mul_f32_e32 v59, v59, v172
	v_cvt_pk_bf16_f32 v60, v60, v61
	v_cvt_pk_bf16_f32 v61, v62, v63
	v_cvt_pk_bf16_f32 v62, v56, v57
	v_cvt_pk_bf16_f32 v63, v58, v59
	global_store_dwordx4 v[128:129], v[60:63], off
	v_mul_f32_e32 v124, v124, v172
	v_mul_f32_e32 v125, v125, v172
	v_mul_f32_e32 v126, v126, v172
	v_mul_f32_e32 v127, v127, v172
	v_mul_f32_e32 v120, v120, v172
	v_mul_f32_e32 v121, v121, v172
	v_mul_f32_e32 v122, v122, v172
	v_mul_f32_e32 v123, v123, v172
	v_cvt_pk_bf16_f32 v124, v124, v125
	v_cvt_pk_bf16_f32 v125, v126, v127
	v_cvt_pk_bf16_f32 v126, v120, v121
	v_cvt_pk_bf16_f32 v127, v122, v123
	global_store_dwordx4 v[128:129], v[124:127], off offset:256
	v_lshl_add_u64 v[128:129], v[128:129], 0, s[100:101]
	v_mul_f32_e32 v52, v52, v170
	v_mul_f32_e32 v53, v53, v170
	v_mul_f32_e32 v54, v54, v170
	v_mul_f32_e32 v55, v55, v170
	v_mul_f32_e32 v48, v48, v170
	v_mul_f32_e32 v49, v49, v170
	v_mul_f32_e32 v50, v50, v170
	v_mul_f32_e32 v51, v51, v170
	v_cvt_pk_bf16_f32 v52, v52, v53
	v_cvt_pk_bf16_f32 v53, v54, v55
	v_cvt_pk_bf16_f32 v54, v48, v49
	v_cvt_pk_bf16_f32 v55, v50, v51
	global_store_dwordx4 v[128:129], v[52:55], off
	v_mul_f32_e32 v116, v116, v170
	v_mul_f32_e32 v117, v117, v170
	v_mul_f32_e32 v118, v118, v170
	v_mul_f32_e32 v119, v119, v170
	v_mul_f32_e32 v112, v112, v170
	v_mul_f32_e32 v113, v113, v170
	v_mul_f32_e32 v114, v114, v170
	v_mul_f32_e32 v115, v115, v170
	v_cvt_pk_bf16_f32 v116, v116, v117
	v_cvt_pk_bf16_f32 v117, v118, v119
	v_cvt_pk_bf16_f32 v118, v112, v113
	v_cvt_pk_bf16_f32 v119, v114, v115
	global_store_dwordx4 v[128:129], v[116:119], off offset:256
	v_lshl_add_u64 v[128:129], v[128:129], 0, s[100:101]
	v_mul_f32_e32 v44, v44, v168
	v_mul_f32_e32 v45, v45, v168
	v_mul_f32_e32 v46, v46, v168
	v_mul_f32_e32 v47, v47, v168
	v_mul_f32_e32 v40, v40, v168
	v_mul_f32_e32 v41, v41, v168
	v_mul_f32_e32 v42, v42, v168
	v_mul_f32_e32 v43, v43, v168
	v_cvt_pk_bf16_f32 v44, v44, v45
	v_cvt_pk_bf16_f32 v45, v46, v47
	v_cvt_pk_bf16_f32 v46, v40, v41
	v_cvt_pk_bf16_f32 v47, v42, v43
	global_store_dwordx4 v[128:129], v[44:47], off
	v_mul_f32_e32 v108, v108, v168
	v_mul_f32_e32 v109, v109, v168
	v_mul_f32_e32 v110, v110, v168
	v_mul_f32_e32 v111, v111, v168
	v_mul_f32_e32 v104, v104, v168
	v_mul_f32_e32 v105, v105, v168
	v_mul_f32_e32 v106, v106, v168
	v_mul_f32_e32 v107, v107, v168
	v_cvt_pk_bf16_f32 v108, v108, v109
	v_cvt_pk_bf16_f32 v109, v110, v111
	v_cvt_pk_bf16_f32 v110, v104, v105
	v_cvt_pk_bf16_f32 v111, v106, v107
	global_store_dwordx4 v[128:129], v[108:111], off offset:256
	v_lshl_add_u64 v[128:129], v[128:129], 0, s[100:101]
	v_mul_f32_e32 v36, v36, v166
	v_mul_f32_e32 v37, v37, v166
	v_mul_f32_e32 v38, v38, v166
	v_mul_f32_e32 v39, v39, v166
	v_mul_f32_e32 v32, v32, v166
	v_mul_f32_e32 v33, v33, v166
	v_mul_f32_e32 v34, v34, v166
	v_mul_f32_e32 v35, v35, v166
	v_cvt_pk_bf16_f32 v36, v36, v37
	v_cvt_pk_bf16_f32 v37, v38, v39
	v_cvt_pk_bf16_f32 v38, v32, v33
	v_cvt_pk_bf16_f32 v39, v34, v35
	global_store_dwordx4 v[128:129], v[36:39], off
	v_mul_f32_e32 v100, v100, v166
	v_mul_f32_e32 v101, v101, v166
	v_mul_f32_e32 v102, v102, v166
	v_mul_f32_e32 v103, v103, v166
	v_mul_f32_e32 v96, v96, v166
	v_mul_f32_e32 v97, v97, v166
	v_mul_f32_e32 v98, v98, v166
	v_mul_f32_e32 v99, v99, v166
	v_cvt_pk_bf16_f32 v100, v100, v101
	v_cvt_pk_bf16_f32 v101, v102, v103
	v_cvt_pk_bf16_f32 v102, v96, v97
	v_cvt_pk_bf16_f32 v103, v98, v99
	global_store_dwordx4 v[128:129], v[100:103], off offset:256
	s_mov_b64 s[100:101], 0x96000
	v_lshl_add_u64 v[128:129], v[128:129], 0, s[100:101]
	s_mov_b64 s[100:101], 0x1e000
	v_mul_f32_e32 v28, v28, v162
	v_mul_f32_e32 v29, v29, v162
	v_mul_f32_e32 v30, v30, v162
	v_mul_f32_e32 v31, v31, v162
	v_mul_f32_e32 v24, v24, v162
	v_mul_f32_e32 v25, v25, v162
	v_mul_f32_e32 v26, v26, v162
	v_mul_f32_e32 v27, v27, v162
	v_cvt_pk_bf16_f32 v28, v28, v29
	v_cvt_pk_bf16_f32 v29, v30, v31
	v_cvt_pk_bf16_f32 v30, v24, v25
	v_cvt_pk_bf16_f32 v31, v26, v27
	global_store_dwordx4 v[128:129], v[28:31], off
	v_mul_f32_e32 v92, v92, v162
	v_mul_f32_e32 v93, v93, v162
	v_mul_f32_e32 v94, v94, v162
	v_mul_f32_e32 v95, v95, v162
	v_mul_f32_e32 v88, v88, v162
	v_mul_f32_e32 v89, v89, v162
	v_mul_f32_e32 v90, v90, v162
	v_mul_f32_e32 v91, v91, v162
	v_cvt_pk_bf16_f32 v92, v92, v93
	v_cvt_pk_bf16_f32 v93, v94, v95
	v_cvt_pk_bf16_f32 v94, v88, v89
	v_cvt_pk_bf16_f32 v95, v90, v91
	global_store_dwordx4 v[128:129], v[92:95], off offset:256
	v_lshl_add_u64 v[128:129], v[128:129], 0, s[100:101]
	v_mul_f32_e32 v20, v20, v160
	v_mul_f32_e32 v21, v21, v160
	v_mul_f32_e32 v22, v22, v160
	v_mul_f32_e32 v23, v23, v160
	v_mul_f32_e32 v16, v16, v160
	v_mul_f32_e32 v17, v17, v160
	v_mul_f32_e32 v18, v18, v160
	v_mul_f32_e32 v19, v19, v160
	v_cvt_pk_bf16_f32 v20, v20, v21
	v_cvt_pk_bf16_f32 v21, v22, v23
	v_cvt_pk_bf16_f32 v22, v16, v17
	v_cvt_pk_bf16_f32 v23, v18, v19
	global_store_dwordx4 v[128:129], v[20:23], off
	v_mul_f32_e32 v84, v84, v160
	v_mul_f32_e32 v85, v85, v160
	v_mul_f32_e32 v86, v86, v160
	v_mul_f32_e32 v87, v87, v160
	v_mul_f32_e32 v80, v80, v160
	v_mul_f32_e32 v81, v81, v160
	v_mul_f32_e32 v82, v82, v160
	v_mul_f32_e32 v83, v83, v160
	v_cvt_pk_bf16_f32 v84, v84, v85
	v_cvt_pk_bf16_f32 v85, v86, v87
	v_cvt_pk_bf16_f32 v86, v80, v81
	v_cvt_pk_bf16_f32 v87, v82, v83
	global_store_dwordx4 v[128:129], v[84:87], off offset:256
	v_lshl_add_u64 v[128:129], v[128:129], 0, s[100:101]
	v_mul_f32_e32 v12, v12, v158
	v_mul_f32_e32 v13, v13, v158
	v_mul_f32_e32 v14, v14, v158
	v_mul_f32_e32 v15, v15, v158
	v_mul_f32_e32 v8, v8, v158
	v_mul_f32_e32 v9, v9, v158
	v_mul_f32_e32 v10, v10, v158
	v_mul_f32_e32 v11, v11, v158
	v_cvt_pk_bf16_f32 v12, v12, v13
	v_cvt_pk_bf16_f32 v13, v14, v15
	v_cvt_pk_bf16_f32 v14, v8, v9
	v_cvt_pk_bf16_f32 v15, v10, v11
	global_store_dwordx4 v[128:129], v[12:15], off
	v_mul_f32_e32 v76, v76, v158
	v_mul_f32_e32 v77, v77, v158
	v_mul_f32_e32 v78, v78, v158
	v_mul_f32_e32 v79, v79, v158
	v_mul_f32_e32 v72, v72, v158
	v_mul_f32_e32 v73, v73, v158
	v_mul_f32_e32 v74, v74, v158
	v_mul_f32_e32 v75, v75, v158
	v_cvt_pk_bf16_f32 v76, v76, v77
	v_cvt_pk_bf16_f32 v77, v78, v79
	v_cvt_pk_bf16_f32 v78, v72, v73
	v_cvt_pk_bf16_f32 v79, v74, v75
	global_store_dwordx4 v[128:129], v[76:79], off offset:256
	v_lshl_add_u64 v[128:129], v[128:129], 0, s[100:101]
	v_mul_f32_e32 v4, v4, v156
	v_mul_f32_e32 v5, v5, v156
	v_mul_f32_e32 v6, v6, v156
	v_mul_f32_e32 v7, v7, v156
	v_mul_f32_e32 v0, v0, v156
	v_mul_f32_e32 v1, v1, v156
	v_mul_f32_e32 v2, v2, v156
	v_mul_f32_e32 v3, v3, v156
	v_cvt_pk_bf16_f32 v4, v4, v5
	v_cvt_pk_bf16_f32 v5, v6, v7
	v_cvt_pk_bf16_f32 v6, v0, v1
	v_cvt_pk_bf16_f32 v7, v2, v3
	global_store_dwordx4 v[128:129], v[4:7], off
	v_mul_f32_e32 v68, v68, v156
	v_mul_f32_e32 v69, v69, v156
	v_mul_f32_e32 v70, v70, v156
	v_mul_f32_e32 v71, v71, v156
	v_mul_f32_e32 v64, v64, v156
	v_mul_f32_e32 v65, v65, v156
	v_mul_f32_e32 v66, v66, v156
	v_mul_f32_e32 v67, v67, v156
	v_cvt_pk_bf16_f32 v68, v68, v69
	v_cvt_pk_bf16_f32 v69, v70, v71
	v_cvt_pk_bf16_f32 v70, v64, v65
	v_cvt_pk_bf16_f32 v71, v66, v67
	global_store_dwordx4 v[128:129], v[68:71], off offset:256
	s_branch .LBB0_271
